# GEMM mainloop: per-phase priority toggles replaced by one static raise for waves 4-7
# speedup vs baseline: 1.0101x; 1.0101x over previous
; #define PG8_STAGE(bufoff, gbase, voff) do { _Pragma("unroll") for (int _i = 0; _i < 2; ++_i) \
;         __builtin_amdgcn_global_load_lds((const unsigned*)((const char*)(gbase) + (voff)[_i]), (LAS unsigned*)(lds + (bufoff) + ldsw + _i * 8192), 16, 0, 0); } while (0)
; #define PG8_BAR __builtin_amdgcn_s_barrier()
; __device__ __forceinline__ void gemm_phase(LAS unsigned char* lds, const Gemm g, const StaticOrder& S, const EpiD& E, const int tid) {
;     ...
;     for (int i = 0; i < 2; ++i) { int R, C; stage_rc(tid * 16 + i * 8192, R, C); const int Rb = EpiD::PERM ? ((R & ~31) + perm32(R & 31)) : R;
;         voffA[i] = (unsigned)(R * g.lda + C) * 2u; voffB[i] = (unsigned)(Rb * g.ldb + C) * 2u; }
;     const size_t kstep = (size_t)(BK * 2);
;     const size_t hstepA = (size_t)HALF * g.lda * 2, hstepB = (size_t)HALF * g.ldb * 2;
;     const size_t tstepA = 2 * hstepA, tstepB = 2 * hstepB;
;     const unsigned ldsw = (unsigned)wid * 1024u;
;     const int aoff = lds_byte(wr * 64 + fr, fq * 8), boff = lds_byte(wc * 32 + fr, fq * 8);
;     ...
;     Unit cur, nxt; int ui = 0;
;     if (!S.next(0, cur)) return;
;     f32x4 acc[2][2][4][2];
; #pragma unroll
;     for (int a = 0; a < 2; ++a)
; #pragma unroll
;         for (int b = 0; b < 2; ++b)
; #pragma unroll
;             for (int m = 0; m < 4; ++m)
; #pragma unroll
;                 for (int n = 0; n < 2; ++n) acc[a][b][m][n] = (f32x4){0.f, 0.f, 0.f, 0.f};
;     bf16x8 At[4][2], B0[2][2], B1[2][2];
;     const char* cA = (const char*)g.A + (size_t)cur.pm * tstepA; const char* cB = (const char*)g.Bt + (size_t)cur.pn * tstepB;
;     PG8_STAGE(PG8_SB(0, 0), cB, voffB); PG8_STAGE(PG8_SA(0, 0), cA, voffA); PG8_STAGE(PG8_SB(0, 1), cB + hstepB, voffB); PG8_STAGE(PG8_SA(0, 1), cA + hstepA, voffA);
;     if (wr == 1) PG8_BAR;
.LBB0_463:
	s_add_u32 s92, s48, s4
	s_addc_u32 s93, s49, s5
	s_add_u32 s94, s48, s10
	v_mul_lo_u32 v0, s12, v133
	s_mov_b32 s13, s31
	s_addc_u32 s95, s49, s11
	v_add_lshl_u32 v16, v0, v135, 1
	v_mul_lo_u32 v0, s12, v182
	s_lshl_b64 s[52:53], s[12:13], 9
	s_ashr_i32 s2, s70, 31
	v_add_lshl_u32 v18, v0, v135, 1
	v_mul_lo_u32 v0, s12, v183
	s_mul_i32 s2, s52, s2
	s_mul_hi_u32 s3, s52, s70
	s_ashr_i32 s11, s7, 31
	v_add_lshl_u32 v136, v0, v184, 1
	v_mul_lo_u32 v0, s12, v185
	s_lshl_b64 s[50:51], s[12:13], 8
	s_add_i32 s2, s3, s2
	s_lshr_b32 s3, s12, 23
	s_mul_i32 s11, s52, s11
	s_mul_hi_u32 s12, s52, s7
	s_ashr_i32 s5, s91, 6
	s_mul_i32 s10, s3, s70
	s_add_i32 s11, s12, s11
	s_mul_i32 s3, s3, s7
	s_ashr_i32 s4, s91, 8
	s_lshl_b32 s96, s5, 10
	s_add_i32 s2, s2, s10
	s_add_i32 s11, s11, s3
	s_mul_i32 s3, s52, s7
	s_add_u32 s14, s94, s3
	s_addc_u32 s15, s95, s11
	s_add_i32 s97, s96, 0
	s_add_i32 m0, s97, 0x10000
	s_mul_i32 s10, s52, s70
	global_load_lds_dwordx4 v18, s[14:15]
	s_add_i32 m0, s97, 0x12000
	v_add_lshl_u32 v138, v0, v184, 1
	s_add_u32 s12, s92, s10
	global_load_lds_dwordx4 v138, s[14:15]
	s_addc_u32 s13, s93, s2
	s_mov_b32 m0, s97
	s_add_i32 s98, s97, 0x2000
	global_load_lds_dwordx4 v16, s[12:13]
	s_mov_b32 m0, s98
	s_add_u32 s2, s14, s50
	global_load_lds_dwordx4 v136, s[12:13]
	s_addc_u32 s3, s15, s51
	s_add_i32 m0, s97, 0x14000
	s_nop 0
	global_load_lds_dwordx4 v18, s[2:3]
	s_add_i32 m0, s97, 0x16000
	s_add_u32 s10, s12, s50
	s_addc_u32 s11, s13, s51
	s_add_i32 s99, s97, 0x4000
	global_load_lds_dwordx4 v138, s[2:3]
	s_mov_b32 m0, s99
	s_add_i32 s72, s97, 0x6000
	global_load_lds_dwordx4 v16, s[10:11]
	s_mov_b32 m0, s72
	s_cmp_lg_u32 s4, 1
	global_load_lds_dwordx4 v136, s[10:11]
	s_cbranch_scc1 .LBB0_465
	s_barrier
	s_setprio 1

; #define PG8_STAGE(bufoff, gbase, voff) do { _Pragma("unroll") for (int _i = 0; _i < 2; ++_i) \
;         __builtin_amdgcn_global_load_lds((const unsigned*)((const char*)(gbase) + (voff)[_i]), (LAS unsigned*)(lds + (bufoff) + ldsw + _i * 8192), 16, 0, 0); } while (0)
; #define PG8_LDA(dst, b, h) do { _Pragma("unroll") for (int m = 0; m < 4; ++m) _Pragma("unroll") for (int k = 0; k < 2; ++k) dst[m][k] = *(const LAS bf16x8*)(lds + PG8_SA(b, h) + aoff + m * 2048 + k * 1024); } while (0)
; #define PG8_LDB(dst, b, h) do { _Pragma("unroll") for (int n = 0; n < 2; ++n) _Pragma("unroll") for (int k = 0; k < 2; ++k) dst[n][k] = *(const LAS bf16x8*)(lds + PG8_SB(b, h) + boff + n * 2048 + k * 1024); } while (0)
; #define PG8_MMA(ai, bj, At, Bt) do { __builtin_amdgcn_s_setprio(1); _Pragma("unroll") for (int m = 0; m < 4; ++m) _Pragma("unroll") for (int n = 0; n < 2; ++n) _Pragma("unroll") for (int k = 0; k < 2; ++k) \
;         acc[ai][bj][m][n] = __builtin_amdgcn_mfma_f32_16x16x32_bf16(Bt[n][k], At[m][k], acc[ai][bj][m][n], 0, 0, 0); __builtin_amdgcn_s_setprio(0); } while (0)
; #define PG8_WAIT_L(n) asm volatile("s_waitcnt lgkmcnt(" #n ")" ::: "memory")
; #define PG8_BAR __builtin_amdgcn_s_barrier()
; #define PG8_SCHED __builtin_amdgcn_sched_barrier(0)
; __device__ __forceinline__ void gemm_phase(LAS unsigned char* lds, const Gemm g, const StaticOrder& S, const EpiD& E, const int tid) {
;     ...
;             PG8_LDB(B0, 0, 0); PG8_SCHED; PG8_LDA(At, 0, 0); PG8_STAGE(PG8_SA(1, 1), a1 + hstepA, voffA);
;             PG8_WAIT_L(8); PG8_BAR; PG8_WAIT_L(0); PG8_MMA(0, 0, At, B0); PG8_BAR; PG8_SCHED;
;             PG8_LDB(B1, 0, 1); PG8_STAGE(PG8_SB(0, 0), b2, voffB);
;             PG8_BAR; PG8_WAIT_L(0); PG8_MMA(0, 1, At, B1); PG8_BAR;
;             PG8_LDA(At, 0, 1); PG8_STAGE(PG8_SA(0, 0), a2, voffA);
;             PG8_BAR; PG8_WAIT_L(0); PG8_MMA(1, 0, At, B0); PG8_BAR; PG8_SCHED;
.LBB0_475:
	s_add_i32 s20, s14, 2
	s_add_u32 s16, s12, 0x80
	s_addc_u32 s15, s13, 0
	s_add_i32 s21, 0, 0x10000
	v_add_u32_e32 v156, s21, v191
	ds_read_b128 v[144:147], v156
	ds_read_b128 v[148:151], v156 offset:1024
	ds_read_b128 v[152:155], v156 offset:2048
	ds_read_b128 v[156:159], v156 offset:3072
	s_cmp_eq_u32 s75, s14
	s_cselect_b32 s14, s2, s16
	s_cselect_b32 s15, s3, s15
	s_cselect_b32 s17, s5, s19
	s_cselect_b32 s16, s4, s18
	v_lshl_add_u64 v[226:227], s[12:13], 0, v[140:141]
	s_add_i32 m0, s97, 0xc000
	ds_read_b128 v[194:197], v193
	ds_read_b128 v[198:201], v193 offset:1024
	ds_read_b128 v[202:205], v193 offset:2048
	ds_read_b128 v[206:209], v193 offset:3072
	ds_read_b128 v[210:213], v193 offset:4096
	ds_read_b128 v[214:217], v193 offset:5120
	ds_read_b128 v[218:221], v193 offset:6144
	ds_read_b128 v[222:225], v193 offset:7168
	global_load_lds_dwordx4 v[226:227], off
	v_lshl_add_u64 v[226:227], s[12:13], 0, v[142:143]
	s_add_i32 m0, s97, 0xe000
	s_nop 0
	global_load_lds_dwordx4 v[226:227], off
	s_waitcnt lgkmcnt(8)
	s_barrier
	s_waitcnt lgkmcnt(0)
	s_waitcnt lgkmcnt(0)
	v_mfma_f32_16x16x32_bf16 v[128:131], v[144:147], v[194:197], v[128:131]
	v_mfma_f32_16x16x32_bf16 v[124:127], v[152:155], v[194:197], v[124:127]
	v_mfma_f32_16x16x32_bf16 v[112:115], v[144:147], v[202:205], v[112:115]
	v_mfma_f32_16x16x32_bf16 v[108:111], v[152:155], v[202:205], v[108:111]
	v_mfma_f32_16x16x32_bf16 v[96:99], v[144:147], v[210:213], v[96:99]
	v_mfma_f32_16x16x32_bf16 v[92:95], v[152:155], v[210:213], v[92:95]
	v_mfma_f32_16x16x32_bf16 v[80:83], v[144:147], v[218:221], v[80:83]
	v_mfma_f32_16x16x32_bf16 v[76:79], v[152:155], v[218:221], v[76:79]
	v_mfma_f32_16x16x32_bf16 v[128:131], v[148:151], v[198:201], v[128:131]
	v_mfma_f32_16x16x32_bf16 v[124:127], v[156:159], v[198:201], v[124:127]
	v_mfma_f32_16x16x32_bf16 v[112:115], v[148:151], v[206:209], v[112:115]
	v_mfma_f32_16x16x32_bf16 v[108:111], v[156:159], v[206:209], v[108:111]
	v_mfma_f32_16x16x32_bf16 v[96:99], v[148:151], v[214:217], v[96:99]
	v_mfma_f32_16x16x32_bf16 v[92:95], v[156:159], v[214:217], v[92:95]
	v_mfma_f32_16x16x32_bf16 v[80:83], v[148:151], v[222:225], v[80:83]
	v_mfma_f32_16x16x32_bf16 v[76:79], v[156:159], v[222:225], v[76:79]
	s_barrier
	s_add_i32 s22, 0, 0x14000
	s_add_i32 s21, s21, s96
	v_add_u32_e32 v238, s22, v191
	v_lshl_add_u64 v[242:243], s[16:17], 0, v[18:19]
	s_mov_b32 m0, s21
	ds_read_b128 v[226:229], v238
	ds_read_b128 v[230:233], v238 offset:1024
	ds_read_b128 v[234:237], v238 offset:2048
	ds_read_b128 v[238:241], v238 offset:3072
	global_load_lds_dwordx4 v[242:243], off
	v_lshl_add_u64 v[244:245], s[16:17], 0, v[138:139]
	s_add_i32 m0, s21, 0x2000
	s_nop 0
	global_load_lds_dwordx4 v[244:245], off
	s_barrier
	s_waitcnt lgkmcnt(0)
	s_waitcnt lgkmcnt(0)
	v_mfma_f32_16x16x32_bf16 v[120:123], v[226:229], v[194:197], v[120:123]
	v_mfma_f32_16x16x32_bf16 v[116:119], v[234:237], v[194:197], v[116:119]
	v_mfma_f32_16x16x32_bf16 v[104:107], v[226:229], v[202:205], v[104:107]
	v_mfma_f32_16x16x32_bf16 v[100:103], v[234:237], v[202:205], v[100:103]
	v_mfma_f32_16x16x32_bf16 v[88:91], v[226:229], v[210:213], v[88:91]
	v_mfma_f32_16x16x32_bf16 v[84:87], v[234:237], v[210:213], v[84:87]
	v_mfma_f32_16x16x32_bf16 v[72:75], v[226:229], v[218:221], v[72:75]
	v_mfma_f32_16x16x32_bf16 v[68:71], v[234:237], v[218:221], v[68:71]
	v_mfma_f32_16x16x32_bf16 v[120:123], v[230:233], v[198:201], v[120:123]
	v_mfma_f32_16x16x32_bf16 v[116:119], v[238:241], v[198:201], v[116:119]
	v_mfma_f32_16x16x32_bf16 v[104:107], v[230:233], v[206:209], v[104:107]
	v_mfma_f32_16x16x32_bf16 v[100:103], v[238:241], v[206:209], v[100:103]
	v_mfma_f32_16x16x32_bf16 v[88:91], v[230:233], v[214:217], v[88:91]
	v_mfma_f32_16x16x32_bf16 v[84:87], v[238:241], v[214:217], v[84:87]
	v_mfma_f32_16x16x32_bf16 v[72:75], v[230:233], v[222:225], v[72:75]
	v_mfma_f32_16x16x32_bf16 v[68:71], v[238:241], v[222:225], v[68:71]
	s_mov_b32 m0, s97
	v_lshl_add_u64 v[246:247], s[14:15], 0, v[16:17]
	s_barrier
	ds_read_b128 v[194:197], v193 offset:16384
	ds_read_b128 v[198:201], v193 offset:17408
	ds_read_b128 v[202:205], v193 offset:18432
	ds_read_b128 v[206:209], v193 offset:19456
	ds_read_b128 v[210:213], v193 offset:20480
	ds_read_b128 v[214:217], v193 offset:21504
	ds_read_b128 v[218:221], v193 offset:22528
	ds_read_b128 v[222:225], v193 offset:23552
	global_load_lds_dwordx4 v[246:247], off
	v_lshl_add_u64 v[248:249], s[14:15], 0, v[136:137]
	s_mov_b32 m0, s98
	s_nop 0
	global_load_lds_dwordx4 v[248:249], off
	s_barrier
	s_waitcnt lgkmcnt(0)
	s_waitcnt lgkmcnt(0)
	v_mfma_f32_16x16x32_bf16 v[64:67], v[144:147], v[194:197], v[64:67]
	v_mfma_f32_16x16x32_bf16 v[60:63], v[152:155], v[194:197], v[60:63]
	v_mfma_f32_16x16x32_bf16 v[48:51], v[144:147], v[202:205], v[48:51]
	v_mfma_f32_16x16x32_bf16 v[44:47], v[152:155], v[202:205], v[44:47]
	v_mfma_f32_16x16x32_bf16 v[32:35], v[144:147], v[210:213], v[32:35]
	v_mfma_f32_16x16x32_bf16 v[28:31], v[152:155], v[210:213], v[28:31]
	v_mfma_f32_16x16x32_bf16 v[12:15], v[144:147], v[218:221], v[12:15]
	v_mfma_f32_16x16x32_bf16 v[8:11], v[152:155], v[218:221], v[8:11]
	v_mfma_f32_16x16x32_bf16 v[64:67], v[148:151], v[198:201], v[64:67]
	v_mfma_f32_16x16x32_bf16 v[60:63], v[156:159], v[198:201], v[60:63]
	v_mfma_f32_16x16x32_bf16 v[48:51], v[148:151], v[206:209], v[48:51]
	v_mfma_f32_16x16x32_bf16 v[44:47], v[156:159], v[206:209], v[44:47]
	v_mfma_f32_16x16x32_bf16 v[32:35], v[148:151], v[214:217], v[32:35]
	v_mfma_f32_16x16x32_bf16 v[28:31], v[156:159], v[214:217], v[28:31]
	v_mfma_f32_16x16x32_bf16 v[12:15], v[148:151], v[222:225], v[12:15]
	v_mfma_f32_16x16x32_bf16 v[8:11], v[156:159], v[222:225], v[8:11]
	s_barrier
; #define PG8_STAGE(bufoff, gbase, voff) do { _Pragma("unroll") for (int _i = 0; _i < 2; ++_i) \
;         __builtin_amdgcn_global_load_lds((const unsigned*)((const char*)(gbase) + (voff)[_i]), (LAS unsigned*)(lds + (bufoff) + ldsw + _i * 8192), 16, 0, 0); } while (0)
; #define PG8_LDA(dst, b, h) do { _Pragma("unroll") for (int m = 0; m < 4; ++m) _Pragma("unroll") for (int k = 0; k < 2; ++k) dst[m][k] = *(const LAS bf16x8*)(lds + PG8_SA(b, h) + aoff + m * 2048 + k * 1024); } while (0)
; #define PG8_LDB(dst, b, h) do { _Pragma("unroll") for (int n = 0; n < 2; ++n) _Pragma("unroll") for (int k = 0; k < 2; ++k) dst[n][k] = *(const LAS bf16x8*)(lds + PG8_SB(b, h) + boff + n * 2048 + k * 1024); } while (0)
; #define PG8_MMA(ai, bj, At, Bt) do { __builtin_amdgcn_s_setprio(1); _Pragma("unroll") for (int m = 0; m < 4; ++m) _Pragma("unroll") for (int n = 0; n < 2; ++n) _Pragma("unroll") for (int k = 0; k < 2; ++k) \
;         acc[ai][bj][m][n] = __builtin_amdgcn_mfma_f32_16x16x32_bf16(Bt[n][k], At[m][k], acc[ai][bj][m][n], 0, 0, 0); __builtin_amdgcn_s_setprio(0); } while (0)
; #define PG8_WAIT_V(n) asm volatile("s_waitcnt vmcnt(" #n ")" ::: "memory")
; #define PG8_WAIT_L(n) asm volatile("s_waitcnt lgkmcnt(" #n ")" ::: "memory")
; #define PG8_BAR __builtin_amdgcn_s_barrier()
; #define PG8_SCHED __builtin_amdgcn_sched_barrier(0)
; __device__ __forceinline__ void gemm_phase(LAS unsigned char* lds, const Gemm g, const StaticOrder& S, const EpiD& E, const int tid) {
;     ...
;             PG8_STAGE(PG8_SB(0, 1), b2 + hstepB, voffB);
;             PG8_WAIT_V(6); PG8_BAR; PG8_MMA(1, 1, At, B1); PG8_BAR;
;             PG8_LDB(B0, 1, 0); PG8_SCHED; PG8_LDA(At, 1, 0); PG8_STAGE(PG8_SA(0, 1), a2 + hstepA, voffA);
;             PG8_WAIT_L(8); PG8_BAR; PG8_WAIT_L(0); PG8_MMA(0, 0, At, B0); PG8_BAR; PG8_SCHED;
;             PG8_LDB(B1, 1, 1); PG8_STAGE(PG8_SB(1, 0), b3, voffB);
	s_add_u32 s16, s16, s50
	s_addc_u32 s17, s17, s51
	s_add_i32 s21, s22, s96
	v_lshl_add_u64 v[250:251], s[16:17], 0, v[18:19]
	s_mov_b32 m0, s21
	v_lshl_add_u64 v[252:253], s[16:17], 0, v[138:139]
	global_load_lds_dwordx4 v[250:251], off
	s_add_i32 m0, s21, 0x2000
	s_nop 0
	global_load_lds_dwordx4 v[252:253], off
	s_waitcnt vmcnt(6)
	s_barrier
	v_mfma_f32_16x16x32_bf16 v[56:59], v[226:229], v[194:197], v[56:59]
	v_mfma_f32_16x16x32_bf16 v[52:55], v[234:237], v[194:197], v[52:55]
	v_mfma_f32_16x16x32_bf16 v[40:43], v[226:229], v[202:205], v[40:43]
	v_mfma_f32_16x16x32_bf16 v[36:39], v[234:237], v[202:205], v[36:39]
	v_mfma_f32_16x16x32_bf16 v[24:27], v[226:229], v[210:213], v[24:27]
	v_mfma_f32_16x16x32_bf16 v[20:23], v[234:237], v[210:213], v[20:23]
	v_mfma_f32_16x16x32_bf16 v[4:7], v[226:229], v[218:221], v[4:7]
	v_mfma_f32_16x16x32_bf16 v[0:3], v[234:237], v[218:221], v[0:3]
	v_mfma_f32_16x16x32_bf16 v[56:59], v[230:233], v[198:201], v[56:59]
	v_mfma_f32_16x16x32_bf16 v[52:55], v[238:241], v[198:201], v[52:55]
	v_mfma_f32_16x16x32_bf16 v[40:43], v[230:233], v[206:209], v[40:43]
	v_mfma_f32_16x16x32_bf16 v[36:39], v[238:241], v[206:209], v[36:39]
	v_mfma_f32_16x16x32_bf16 v[24:27], v[230:233], v[214:217], v[24:27]
	v_mfma_f32_16x16x32_bf16 v[20:23], v[238:241], v[214:217], v[20:23]
	v_mfma_f32_16x16x32_bf16 v[4:7], v[230:233], v[222:225], v[4:7]
	v_mfma_f32_16x16x32_bf16 v[0:3], v[238:241], v[222:225], v[0:3]
	s_add_i32 s16, 0, 0x18000
	v_add_u32_e32 v156, s16, v191
	s_barrier
	ds_read_b128 v[144:147], v156
	ds_read_b128 v[148:151], v156 offset:1024
	ds_read_b128 v[152:155], v156 offset:2048
	ds_read_b128 v[156:159], v156 offset:3072
	s_add_u32 s14, s14, s50
	s_addc_u32 s15, s15, s51
	s_mov_b32 m0, s99
	v_lshl_add_u64 v[226:227], s[14:15], 0, v[16:17]
	ds_read_b128 v[194:197], v193 offset:32768
	ds_read_b128 v[198:201], v193 offset:33792
	ds_read_b128 v[202:205], v193 offset:34816
	ds_read_b128 v[206:209], v193 offset:35840
	ds_read_b128 v[210:213], v193 offset:36864
	ds_read_b128 v[214:217], v193 offset:37888
	ds_read_b128 v[218:221], v193 offset:38912
	ds_read_b128 v[222:225], v193 offset:39936
	global_load_lds_dwordx4 v[226:227], off
	v_lshl_add_u64 v[226:227], s[14:15], 0, v[136:137]
	s_mov_b32 m0, s72
	s_nop 0
	global_load_lds_dwordx4 v[226:227], off
	s_waitcnt lgkmcnt(8)
	s_barrier
	s_waitcnt lgkmcnt(0)
	s_waitcnt lgkmcnt(0)
	v_mfma_f32_16x16x32_bf16 v[128:131], v[144:147], v[194:197], v[128:131]
	v_mfma_f32_16x16x32_bf16 v[124:127], v[152:155], v[194:197], v[124:127]
	v_mfma_f32_16x16x32_bf16 v[112:115], v[144:147], v[202:205], v[112:115]
	v_mfma_f32_16x16x32_bf16 v[108:111], v[152:155], v[202:205], v[108:111]
	v_mfma_f32_16x16x32_bf16 v[96:99], v[144:147], v[210:213], v[96:99]
	v_mfma_f32_16x16x32_bf16 v[92:95], v[152:155], v[210:213], v[92:95]
	v_mfma_f32_16x16x32_bf16 v[80:83], v[144:147], v[218:221], v[80:83]
	v_mfma_f32_16x16x32_bf16 v[76:79], v[152:155], v[218:221], v[76:79]
	v_mfma_f32_16x16x32_bf16 v[128:131], v[148:151], v[198:201], v[128:131]
	v_mfma_f32_16x16x32_bf16 v[124:127], v[156:159], v[198:201], v[124:127]
	v_mfma_f32_16x16x32_bf16 v[112:115], v[148:151], v[206:209], v[112:115]
	v_mfma_f32_16x16x32_bf16 v[108:111], v[156:159], v[206:209], v[108:111]
	v_mfma_f32_16x16x32_bf16 v[96:99], v[148:151], v[214:217], v[96:99]
	v_mfma_f32_16x16x32_bf16 v[92:95], v[156:159], v[214:217], v[92:95]
	v_mfma_f32_16x16x32_bf16 v[80:83], v[148:151], v[222:225], v[80:83]
	v_mfma_f32_16x16x32_bf16 v[76:79], v[156:159], v[222:225], v[76:79]
	s_barrier
	s_add_i32 s14, 0, 0x1c000
	s_add_i32 s15, s16, s96
	v_add_u32_e32 v238, s14, v191
	v_lshl_add_u64 v[242:243], v[242:243], 0, s[34:35]
	s_mov_b32 m0, s15
	ds_read_b128 v[226:229], v238
	ds_read_b128 v[230:233], v238 offset:1024
	ds_read_b128 v[234:237], v238 offset:2048
	ds_read_b128 v[238:241], v238 offset:3072
	global_load_lds_dwordx4 v[242:243], off
	v_lshl_add_u64 v[242:243], v[244:245], 0, s[34:35]
	s_add_i32 m0, s15, 0x2000
	s_nop 0
	global_load_lds_dwordx4 v[242:243], off
	s_barrier
; #define PG8_STAGE(bufoff, gbase, voff) do { _Pragma("unroll") for (int _i = 0; _i < 2; ++_i) \
;         __builtin_amdgcn_global_load_lds((const unsigned*)((const char*)(gbase) + (voff)[_i]), (LAS unsigned*)(lds + (bufoff) + ldsw + _i * 8192), 16, 0, 0); } while (0)
; #define PG8_LDA(dst, b, h) do { _Pragma("unroll") for (int m = 0; m < 4; ++m) _Pragma("unroll") for (int k = 0; k < 2; ++k) dst[m][k] = *(const LAS bf16x8*)(lds + PG8_SA(b, h) + aoff + m * 2048 + k * 1024); } while (0)
; #define PG8_BAR __builtin_amdgcn_s_barrier()
; __device__ __forceinline__ void build_epi(KA a, int gi, EpiP& E) {
;     ...
;     E.O = nullptr; E.ldc = 1024; E.ncols = 1 << 30; E.rowscale = nullptr; E.colscale = nullptr; E.scal = 1.0f; E.ssq = nullptr; E.act = 0; E.O2 = nullptr; E.b0 = E.b1 = E.b2 = E.b3 = nullptr; E.Olo = nullptr; E.split = 0;
;     switch (gi) {
;     case 0: E.O = (bf16_t*)(ws + WS_PROJ); E.ldc = PROJ_LD; E.ncols = PROJ_LD; E.rowscale = sm + OFF_RS0; break;
;     case 1: E.O = (bf16_t*)(ws + WS_KB); E.ldc = 1024; E.rowscale = sm + OFF_RSM; break;
;     case 2: E.O = (bf16_t*)(ws + WS_VT); E.ldc = TM; E.colscale = sm + OFF_RSM; break;
;     case 3: E.O = (bf16_t*)AOUT; E.ldc = 2048; E.act = 2; E.O2 = (bf16_t*)(ws + WS_GB); E.b0 = AIN(I_W0_F); E.b1 = AIN(I_W0_B); E.b2 = AIN(I_A0_F); E.b3 = AIN(I_A0_B); break;
;     case 9: E.O = (bf16_t*)(ws + WS_GB); E.ldc = 512; break;
;     case 4: E.O = (bf16_t*)(ws + WS_MO); E.ssq = sm + OFF_SSQ1; break;
;     case 5: E.O = (bf16_t*)(ws + WS_Q); E.rowscale = sm + OFF_RS1; E.scal = 0.0625f * 1.44269504f; break;
;     case 6: E.O = (bf16_t*)(ws + WS_XO); E.ssq = sm + OFF_SSQ2; break;
;     case 7: E.O = (bf16_t*)(ws + WS_HID); E.ldc = 4096; E.rowscale = sm + OFF_RS2; E.act = 1; break;
;     default: E.O = (bf16_t*)(ws + WS_FO_HI) - (size_t)FO_SPLIT * 1024; E.Olo = (bf16_t*)(ws + WS_KB); E.split = FO_SPLIT; E.ssq = sm + OFF_SSQ3; break;
; __device__ __forceinline__ void gemm_phase(LAS unsigned char* lds, const Gemm g, const StaticOrder& S, const EpiD& E, const int tid) {
;     ...
;             PG8_BAR; PG8_WAIT_L(0); PG8_MMA(0, 1, At, B1); PG8_BAR;
;             PG8_LDA(At, 1, 1); PG8_STAGE(PG8_SA(1, 0), a3, voffA);
;             PG8_BAR; PG8_WAIT_L(0); PG8_MMA(1, 0, At, B0); PG8_BAR; PG8_SCHED;
;             PG8_STAGE(PG8_SB(1, 1), b3 + hstepB, voffB);
;             PG8_WAIT_V(6); PG8_BAR; PG8_MMA(1, 1, At, B1); PG8_BAR;
;         }
	s_waitcnt lgkmcnt(0)
	s_waitcnt lgkmcnt(0)
	v_mfma_f32_16x16x32_bf16 v[120:123], v[226:229], v[194:197], v[120:123]
	v_mfma_f32_16x16x32_bf16 v[116:119], v[234:237], v[194:197], v[116:119]
	v_mfma_f32_16x16x32_bf16 v[104:107], v[226:229], v[202:205], v[104:107]
	v_mfma_f32_16x16x32_bf16 v[100:103], v[234:237], v[202:205], v[100:103]
	v_mfma_f32_16x16x32_bf16 v[88:91], v[226:229], v[210:213], v[88:91]
	v_mfma_f32_16x16x32_bf16 v[84:87], v[234:237], v[210:213], v[84:87]
	v_mfma_f32_16x16x32_bf16 v[72:75], v[226:229], v[218:221], v[72:75]
	v_mfma_f32_16x16x32_bf16 v[68:71], v[234:237], v[218:221], v[68:71]
	v_mfma_f32_16x16x32_bf16 v[120:123], v[230:233], v[198:201], v[120:123]
	v_mfma_f32_16x16x32_bf16 v[116:119], v[238:241], v[198:201], v[116:119]
	v_mfma_f32_16x16x32_bf16 v[104:107], v[230:233], v[206:209], v[104:107]
	v_mfma_f32_16x16x32_bf16 v[100:103], v[238:241], v[206:209], v[100:103]
	v_mfma_f32_16x16x32_bf16 v[88:91], v[230:233], v[214:217], v[88:91]
	v_mfma_f32_16x16x32_bf16 v[84:87], v[238:241], v[214:217], v[84:87]
	v_mfma_f32_16x16x32_bf16 v[72:75], v[230:233], v[222:225], v[72:75]
	v_mfma_f32_16x16x32_bf16 v[68:71], v[238:241], v[222:225], v[68:71]
	s_mov_b32 m0, s33
	v_lshl_add_u64 v[242:243], v[246:247], 0, s[34:35]
	s_barrier
	ds_read_b128 v[194:197], v193 offset:49152
	ds_read_b128 v[198:201], v193 offset:50176
	ds_read_b128 v[202:205], v193 offset:51200
	ds_read_b128 v[206:209], v193 offset:52224
	ds_read_b128 v[210:213], v193 offset:53248
	ds_read_b128 v[214:217], v193 offset:54272
	ds_read_b128 v[218:221], v193 offset:55296
	ds_read_b128 v[222:225], v193 offset:56320
	global_load_lds_dwordx4 v[242:243], off
	v_lshl_add_u64 v[242:243], v[248:249], 0, s[34:35]
	s_mov_b32 m0, s77
	s_nop 0
	global_load_lds_dwordx4 v[242:243], off
	s_barrier
	s_waitcnt lgkmcnt(0)
	s_waitcnt lgkmcnt(0)
	v_mfma_f32_16x16x32_bf16 v[64:67], v[144:147], v[194:197], v[64:67]
	v_mfma_f32_16x16x32_bf16 v[60:63], v[152:155], v[194:197], v[60:63]
	v_mfma_f32_16x16x32_bf16 v[48:51], v[144:147], v[202:205], v[48:51]
	v_mfma_f32_16x16x32_bf16 v[44:47], v[152:155], v[202:205], v[44:47]
	v_mfma_f32_16x16x32_bf16 v[32:35], v[144:147], v[210:213], v[32:35]
	v_mfma_f32_16x16x32_bf16 v[28:31], v[152:155], v[210:213], v[28:31]
	v_mfma_f32_16x16x32_bf16 v[12:15], v[144:147], v[218:221], v[12:15]
	v_mfma_f32_16x16x32_bf16 v[8:11], v[152:155], v[218:221], v[8:11]
	v_mfma_f32_16x16x32_bf16 v[64:67], v[148:151], v[198:201], v[64:67]
	v_mfma_f32_16x16x32_bf16 v[60:63], v[156:159], v[198:201], v[60:63]
	v_mfma_f32_16x16x32_bf16 v[48:51], v[148:151], v[206:209], v[48:51]
	v_mfma_f32_16x16x32_bf16 v[44:47], v[156:159], v[206:209], v[44:47]
	v_mfma_f32_16x16x32_bf16 v[32:35], v[148:151], v[214:217], v[32:35]
	v_mfma_f32_16x16x32_bf16 v[28:31], v[156:159], v[214:217], v[28:31]
	v_mfma_f32_16x16x32_bf16 v[12:15], v[148:151], v[222:225], v[12:15]
	v_mfma_f32_16x16x32_bf16 v[8:11], v[156:159], v[222:225], v[8:11]
	s_barrier
	s_add_i32 s14, s14, s96
	v_lshl_add_u64 v[144:145], v[250:251], 0, s[34:35]
	s_mov_b32 m0, s14
	s_nop 0
	global_load_lds_dwordx4 v[144:145], off
	v_lshl_add_u64 v[144:145], v[252:253], 0, s[34:35]
	s_add_i32 m0, s14, 0x2000
	s_nop 0
	global_load_lds_dwordx4 v[144:145], off
	s_waitcnt vmcnt(6)
	s_barrier
	v_mfma_f32_16x16x32_bf16 v[56:59], v[226:229], v[194:197], v[56:59]
	v_mfma_f32_16x16x32_bf16 v[52:55], v[234:237], v[194:197], v[52:55]
	v_mfma_f32_16x16x32_bf16 v[40:43], v[226:229], v[202:205], v[40:43]
	v_mfma_f32_16x16x32_bf16 v[36:39], v[234:237], v[202:205], v[36:39]
	v_mfma_f32_16x16x32_bf16 v[24:27], v[226:229], v[210:213], v[24:27]
	v_mfma_f32_16x16x32_bf16 v[20:23], v[234:237], v[210:213], v[20:23]
	v_mfma_f32_16x16x32_bf16 v[4:7], v[226:229], v[218:221], v[4:7]
	v_mfma_f32_16x16x32_bf16 v[0:3], v[234:237], v[218:221], v[0:3]
	v_mfma_f32_16x16x32_bf16 v[56:59], v[230:233], v[198:201], v[56:59]
	v_mfma_f32_16x16x32_bf16 v[52:55], v[238:241], v[198:201], v[52:55]
	v_mfma_f32_16x16x32_bf16 v[40:43], v[230:233], v[206:209], v[40:43]
	v_mfma_f32_16x16x32_bf16 v[36:39], v[238:241], v[206:209], v[36:39]
	v_mfma_f32_16x16x32_bf16 v[24:27], v[230:233], v[214:217], v[24:27]
	v_mfma_f32_16x16x32_bf16 v[20:23], v[238:241], v[214:217], v[20:23]
	v_mfma_f32_16x16x32_bf16 v[4:7], v[230:233], v[222:225], v[4:7]
	v_mfma_f32_16x16x32_bf16 v[0:3], v[238:241], v[222:225], v[0:3]
	s_add_u32 s12, s12, 0x100
	s_addc_u32 s13, s13, 0
	s_add_u32 s18, s18, 0x100
	s_addc_u32 s19, s19, 0
	s_cmp_ge_u32 s20, s88
	s_mov_b32 s14, s20
	s_barrier
	s_cbranch_scc0 .LBB0_475
	s_mov_b32 s29, s87
	s_mov_b64 s[64:65], s[0:1]
	s_load_dwordx2 s[12:13], s[64:65], 0x140
	s_mov_b64 s[20:21], -1
	s_mov_b64 s[18:19], 0
	s_cmp_lt_i32 s29, 4
	s_mov_b64 s[14:15], 0
	s_cbranch_scc1 .LBB0_497
	s_cmp_gt_i32 s29, 5
	s_cbranch_scc0 .LBB0_490
	s_mov_b64 s[54:55], 0
	s_cmp_gt_i32 s29, 6
	s_cbranch_scc0 .LBB0_487
	s_mov_b64 s[16:17], 0
	s_cmp_gt_i32 s29, 8
	s_cbranch_scc0 .LBB0_482
	s_cmp_eq_u32 s29, 9
	s_mov_b64 s[14:15], -1
	s_cbranch_scc0 .LBB0_770
	s_waitcnt lgkmcnt(0)
	s_add_u32 s56, s12, 0x2bc00000
	s_addc_u32 s57, s13, 0
	s_mov_b64 s[14:15], 0
	s_mov_b64 s[20:21], 0

; #define PG8_WAIT_V(n) asm volatile("s_waitcnt vmcnt(" #n ")" ::: "memory")
; #define PG8_BAR __builtin_amdgcn_s_barrier()
; __device__ __forceinline__ void gemm_phase(LAS unsigned char* lds, const Gemm g, const StaticOrder& S, const EpiD& E, const int tid) {
;     ...
;     PG8_WAIT_V(0);
;     if (wr == 0) PG8_BAR;
;     PG8_BAR;
.LBB0_771:
	s_setprio 0
	s_waitcnt vmcnt(0)
	s_cmpk_gt_u32 s91, 0xff
	s_cbranch_scc1 .LBB0_418
	s_barrier
	s_branch .LBB0_418
